# v39 stack + P4 start: SS2 load issued before the GEMM prologue, 1/rms table (RS0) computed by waves 0-3 after the first 8 tile loads are in flight (was: load, wait, sqrt/div, barrier before the prolog
# baseline (speedup 1.0000x reference)
.LBB0_607:
	s_or_b64 exec, exec, s[4:5]
	s_movk_i32 s1, 0x100
	v_cmp_gt_u32_e32 vcc, s1, v0
	s_barrier
	s_and_saveexec_b64 s[18:19], vcc
	s_cbranch_execz .LBB0_609
	v_lshl_or_b32 v240, s0, 8, v0
	v_ashrrev_i32_e32 v241, 31, v240
	v_lshl_add_u64 v[240:241], v[240:241], 4, s[16:17]
	global_load_dwordx4 v[240:243], v[240:241], off

.LBB0_614:
	v_lshlrev_b32_e32 v2, 4, v0
	v_and_b32_e32 v3, 32, v0
	v_lshrrev_b32_e32 v4, 5, v0
	v_bfe_u32 v12, v0, 2, 4
	v_bitop3_b32 v10, v2, v3, 48 bitop3:0x6c
	v_and_b32_e32 v11, 64, v0
	v_and_b32_e32 v13, 24, v187
	v_and_b32_e32 v4, 4, v4
	v_bfe_u32 v5, v0, 2, 2
	v_or_b32_e32 v14, 0x2000, v2
	v_or_b32_e32 v3, v10, v11
	v_or3_b32 v4, v4, v5, v13
	v_and_or_b32 v5, v148, 48, v12
	v_lshrrev_b32_e32 v2, 7, v14
	s_movk_i32 s5, 0x70
	v_lshl_or_b32 v130, v5, 11, v3
	v_and_or_b32 v5, v2, s5, v12
	s_movk_i32 s5, 0x60
	v_and_or_b32 v2, v2, s5, v4
	v_readlane_b32 s5, v251, 61
	s_add_i32 s16, s1, s5
	s_ashr_i32 s1, s16, 31
	s_lshr_b32 s1, s1, 25
	s_add_i32 s17, s16, s1
	s_ashr_i32 s1, s17, 7
	s_lshl_b32 s18, s1, 3
	s_sub_i32 s1, 64, s18
	s_min_i32 s19, s1, 8
	s_abs_i32 s25, s19
	v_and_or_b32 v6, v148, 32, v4
	v_cvt_f32_u32_e32 v4, s25
	v_lshl_or_b32 v136, v2, 11, v3
	s_sub_i32 s27, 0, s25
	s_and_b32 s17, s17, 0xffffff80
	v_rcp_iflag_f32_e32 v2, v4
	s_sub_i32 s16, s16, s17
	s_abs_i32 s26, s16
	s_lshr_b32 s5, s24, 6
	v_mul_f32_e32 v2, 0x4f7ffffe, v2
	v_cvt_u32_f32_e32 v2, v2
	s_xor_b32 s17, s16, s19
	s_lshr_b32 s4, s24, 8
	s_lshl_b32 s1, s5, 10
	v_readfirstlane_b32 s30, v2
	s_mul_i32 s27, s27, s30
	s_mul_hi_u32 s27, s30, s27
	s_add_i32 s30, s30, s27
	s_mul_hi_u32 s27, s26, s30
	s_mul_i32 s30, s27, s25
	s_sub_i32 s26, s26, s30
	s_ashr_i32 s17, s17, 31
	s_add_i32 s30, s27, 1
	s_sub_i32 s31, s26, s25
	s_cmp_ge_u32 s26, s25
	s_cselect_b32 s27, s30, s27
	s_cselect_b32 s26, s31, s26
	s_add_i32 s30, s27, 1
	s_cmp_ge_u32 s26, s25
	s_cselect_b32 s25, s30, s27
	s_xor_b32 s25, s25, s17
	s_sub_i32 s40, s25, s17
	s_mul_i32 s17, s40, s19
	s_sub_i32 s16, s16, s17
	s_add_i32 s42, s18, s16
	s_ashr_i32 s43, s42, 31
	s_ashr_i32 s41, s40, 31
	s_lshl_b64 s[16:17], s[42:43], 19
	s_lshl_b64 s[18:19], s[40:41], 19
	v_readlane_b32 s26, v251, 45
	v_readlane_b32 s27, v251, 46
	s_add_u32 s46, s26, s18
	s_addc_u32 s47, s27, s19
	s_add_i32 s33, s1, 0
	v_lshl_or_b32 v132, v6, 11, v3
	s_add_i32 m0, s33, 0x10000
	v_lshl_or_b32 v134, v5, 11, v3
	global_load_lds_dwordx4 v132, s[46:47]
	s_add_i32 m0, s33, 0x12000
	s_add_u32 s18, s46, 0x40000
	global_load_lds_dwordx4 v136, s[46:47]
	s_addc_u32 s19, s47, 0
	s_add_i32 m0, s33, 0x14000
	v_mov_b32_e32 v133, 0
	global_load_lds_dwordx4 v132, s[18:19]
	s_add_i32 m0, s33, 0x16000
	s_add_u32 s44, s8, s16
	s_addc_u32 s45, s9, s17
	s_add_i32 s41, s33, 0x2000
	global_load_lds_dwordx4 v136, s[18:19]
	s_mov_b32 m0, s33
	s_add_u32 s16, s44, 0x40000
	global_load_lds_dwordx4 v130, s[44:45]
	s_mov_b32 m0, s41
	s_addc_u32 s17, s45, 0
	s_add_i32 s43, s33, 0x4000
	global_load_lds_dwordx4 v134, s[44:45]
	s_mov_b32 m0, s43
	s_add_i32 s50, s33, 0x6000
	global_load_lds_dwordx4 v130, s[16:17]
	s_mov_b32 m0, s50
	v_mov_b32_e32 v137, v133
	global_load_lds_dwordx4 v134, s[16:17]
	v_mov_b32_e32 v131, v133
	v_mov_b32_e32 v135, v133
	v_readfirstlane_b32 s98, v0
	s_cmp_gt_u32 s98, 255
	s_cbranch_scc1 .Lmy_rs4_skip
	v_mov_b32_e32 v246, 0x358637bd
	s_mov_b32 s98, 0xf800000
	s_waitcnt vmcnt(8)
	v_mov_b32_e32 v244, v241
	v_mov_b32_e32 v245, v242
	v_mov_b32_e32 v241, v243
	v_pk_add_f32 v[240:241], v[244:245], v[240:241]
	v_mov_b32_e32 v242, 0x260
	v_add_f32_e32 v240, v240, v241
	v_fmac_f32_e32 v246, 0x3a800000, v240
	v_mul_f32_e32 v240, 0x4f800000, v246
	v_cmp_gt_f32_e32 vcc, s98, v246
	s_nop 1
	v_cndmask_b32_e32 v240, v246, v240, vcc
	v_sqrt_f32_e32 v241, v240
	s_nop 0
	v_add_u32_e32 v243, -1, v241
	v_add_u32_e32 v244, 1, v241
	v_fma_f32 v245, -v243, v241, v240
	v_fma_f32 v246, -v244, v241, v240
	v_cmp_ge_f32_e64 s[100:101], 0, v245
	s_nop 1
	v_cndmask_b32_e64 v241, v241, v243, s[100:101]
	v_cmp_lt_f32_e64 s[100:101], 0, v246
	s_nop 1
	v_cndmask_b32_e64 v241, v241, v244, s[100:101]
	v_mul_f32_e32 v243, 0x37800000, v241
	v_cndmask_b32_e32 v241, v241, v243, vcc
	v_cmp_class_f32_e32 vcc, v240, v242
	s_nop 1
	v_cndmask_b32_e32 v240, v241, v240, vcc
	v_div_scale_f32 v241, s[100:101], v240, v240, 1.0
	v_rcp_f32_e32 v242, v241
	v_div_scale_f32 v243, vcc, 1.0, v240, 1.0
	v_fma_f32 v244, -v241, v242, 1.0
	v_fmac_f32_e32 v242, v244, v242
	v_mul_f32_e32 v244, v243, v242
	v_fma_f32 v245, -v241, v244, v243
	v_fmac_f32_e32 v244, v245, v242
	v_fma_f32 v241, -v241, v244, v243
	v_div_fmas_f32 v241, v241, v242, v244
	v_div_fixup_f32 v240, v241, v240, 1.0
	ds_write_b32 v191, v240
.Lmy_rs4_skip:
	s_cmp_eq_u32 s4, 1
	s_mov_b32 s51, 0
	v_lshl_add_u64 v[8:9], s[46:47], 0, v[132:133]
	v_lshl_add_u64 v[6:7], s[46:47], 0, v[136:137]
	v_lshl_add_u64 v[2:3], s[44:45], 0, v[130:131]
	s_cselect_b64 s[16:17], -1, 0
	s_cmp_lg_u32 s4, 1
	v_lshl_add_u64 v[4:5], s[44:45], 0, v[134:135]
	s_cbranch_scc1 .LBB0_616
	s_barrier
